# 64-bit accumulator zeroing in all 18 GEMM unit headers (on top of hand-written EpiFfnAct and EpiRes epilogues)
# speedup vs baseline: 1.0505x; 1.0020x over previous
.LBB0_744:
	s_ashr_i32 s23, s22, 31
	s_lshl_b64 s[26:27], s[22:23], 17
	s_add_u32 s26, s74, s26
	s_addc_u32 s27, s75, s27
	s_cmp_gt_i32 s20, 3
	s_cselect_b32 s101, 0x100, 0
	s_add_u32 s26, s26, s101
	s_addc_u32 s27, s27, 0
	s_and_b64 s[28:29], s[4:5], exec
	s_cselect_b32 s7, s27, s35
	s_cselect_b32 s23, s26, s34
	s_ashr_i32 s21, s20, 31
	s_lshl_b64 s[28:29], s[20:21], 17
	s_add_u32 s28, s78, s28
	s_addc_u32 s29, s85, s29
	s_add_u32 s28, s28, s101
	s_addc_u32 s29, s29, 0
	s_and_b64 s[38:39], s[4:5], exec
	v_mov_b32_e32 v0, 0
	s_cselect_b32 s21, s29, s9
	s_cselect_b32 s73, s28, s8
	s_mov_b32 s42, 0
	s_mov_b64 s[38:39], 0
	s_mov_b64 s[40:41], -1
	s_waitcnt vmcnt(0)
	v_mov_b32_e32 v1, 0
	v_mov_b64_e32 v[2:3], 0
	v_mov_b64_e32 v[4:5], 0
	v_mov_b64_e32 v[6:7], 0
	v_mov_b64_e32 v[8:9], 0
	v_mov_b64_e32 v[10:11], 0
	v_mov_b64_e32 v[12:13], 0
	v_mov_b64_e32 v[14:15], 0
	v_mov_b64_e32 v[16:17], 0
	v_mov_b64_e32 v[18:19], 0
	v_mov_b64_e32 v[20:21], 0
	v_mov_b64_e32 v[22:23], 0
	v_mov_b64_e32 v[24:25], 0
	v_mov_b64_e32 v[26:27], 0
	v_mov_b64_e32 v[28:29], 0
	v_mov_b64_e32 v[30:31], 0
	v_mov_b64_e32 v[32:33], 0
	v_mov_b64_e32 v[34:35], 0
	v_mov_b64_e32 v[36:37], 0
	v_mov_b64_e32 v[38:39], 0
	v_mov_b64_e32 v[40:41], 0
	v_mov_b64_e32 v[42:43], 0
	v_mov_b64_e32 v[44:45], 0
	v_mov_b64_e32 v[46:47], 0
	v_mov_b64_e32 v[48:49], 0
	v_mov_b64_e32 v[50:51], 0
	v_mov_b64_e32 v[52:53], 0
	v_mov_b64_e32 v[54:55], 0
	v_mov_b64_e32 v[56:57], 0
	v_mov_b64_e32 v[58:59], 0
	v_mov_b64_e32 v[60:61], 0
	v_mov_b64_e32 v[62:63], 0
	v_mov_b64_e32 v[72:73], 0
	v_mov_b64_e32 v[74:75], 0
	v_mov_b64_e32 v[80:81], 0
	v_mov_b64_e32 v[82:83], 0
	v_mov_b64_e32 v[88:89], 0
	v_mov_b64_e32 v[90:91], 0
	v_mov_b64_e32 v[92:93], 0
	v_mov_b64_e32 v[94:95], 0
	v_mov_b64_e32 v[96:97], 0
	v_mov_b64_e32 v[98:99], 0
	v_mov_b64_e32 v[100:101], 0
	v_mov_b64_e32 v[102:103], 0
	v_mov_b64_e32 v[104:105], 0
	v_mov_b64_e32 v[106:107], 0
	v_mov_b64_e32 v[108:109], 0
	v_mov_b64_e32 v[110:111], 0
	v_mov_b64_e32 v[112:113], 0
	v_mov_b64_e32 v[114:115], 0
	v_mov_b64_e32 v[116:117], 0
	v_mov_b64_e32 v[118:119], 0
	v_mov_b64_e32 v[120:121], 0
	v_mov_b64_e32 v[122:123], 0
	v_mov_b64_e32 v[124:125], 0
	v_mov_b64_e32 v[126:127], 0
	v_mov_b64_e32 v[128:129], 0
	v_mov_b64_e32 v[130:131], 0
	v_mov_b64_e32 v[132:133], 0
	v_mov_b64_e32 v[134:135], 0
	v_mov_b64_e32 v[136:137], 0
	v_mov_b64_e32 v[138:139], 0
	v_mov_b64_e32 v[140:141], 0
	v_mov_b64_e32 v[142:143], 0

.LBB0_806:
	s_ashr_i32 s23, s22, 31
	s_lshl_b64 s[30:31], s[22:23], 17
	s_add_u32 s30, s56, s30
	s_addc_u32 s31, s57, s31
	s_and_b32 s101, s22, 1
	s_lshl_b32 s101, s101, 8
	s_add_u32 s30, s30, s101
	s_addc_u32 s31, s31, 0
	s_and_b64 s[6:7], s[6:7], exec
	v_mov_b32_e32 v0, 0
	s_cselect_b32 s23, s31, s35
	s_cselect_b32 s27, s30, s34
	s_mov_b32 s42, 0
	s_mov_b64 s[6:7], 0
	s_mov_b64 s[40:41], -1
	s_waitcnt vmcnt(0)
	v_mov_b32_e32 v1, 0
	v_mov_b64_e32 v[2:3], 0
	v_mov_b64_e32 v[4:5], 0
	v_mov_b64_e32 v[6:7], 0
	v_mov_b64_e32 v[8:9], 0
	v_mov_b64_e32 v[10:11], 0
	v_mov_b64_e32 v[12:13], 0
	v_mov_b64_e32 v[14:15], 0
	v_mov_b64_e32 v[16:17], 0
	v_mov_b64_e32 v[18:19], 0
	v_mov_b64_e32 v[20:21], 0
	v_mov_b64_e32 v[22:23], 0
	v_mov_b64_e32 v[24:25], 0
	v_mov_b64_e32 v[26:27], 0
	v_mov_b64_e32 v[28:29], 0
	v_mov_b64_e32 v[30:31], 0
	v_mov_b64_e32 v[32:33], 0
	v_mov_b64_e32 v[34:35], 0
	v_mov_b64_e32 v[36:37], 0
	v_mov_b64_e32 v[38:39], 0
	v_mov_b64_e32 v[48:49], 0
	v_mov_b64_e32 v[50:51], 0
	v_mov_b64_e32 v[52:53], 0
	v_mov_b64_e32 v[54:55], 0
	v_mov_b64_e32 v[64:65], 0
	v_mov_b64_e32 v[66:67], 0
	v_mov_b64_e32 v[68:69], 0
	v_mov_b64_e32 v[70:71], 0
	v_mov_b64_e32 v[72:73], 0
	v_mov_b64_e32 v[74:75], 0
	v_mov_b64_e32 v[76:77], 0
	v_mov_b64_e32 v[78:79], 0
	v_mov_b64_e32 v[80:81], 0
	v_mov_b64_e32 v[82:83], 0
	v_mov_b64_e32 v[84:85], 0
	v_mov_b64_e32 v[86:87], 0
	v_mov_b64_e32 v[88:89], 0
	v_mov_b64_e32 v[90:91], 0
	v_mov_b64_e32 v[92:93], 0
	v_mov_b64_e32 v[94:95], 0
	v_mov_b64_e32 v[96:97], 0
	v_mov_b64_e32 v[98:99], 0
	v_mov_b64_e32 v[100:101], 0
	v_mov_b64_e32 v[102:103], 0
	v_mov_b64_e32 v[104:105], 0
	v_mov_b64_e32 v[106:107], 0
	v_mov_b64_e32 v[108:109], 0
	v_mov_b64_e32 v[110:111], 0
	v_mov_b64_e32 v[112:113], 0
	v_mov_b64_e32 v[114:115], 0
	v_mov_b64_e32 v[116:117], 0
	v_mov_b64_e32 v[118:119], 0
	v_mov_b64_e32 v[120:121], 0
	v_mov_b64_e32 v[122:123], 0
	v_mov_b64_e32 v[124:125], 0
	v_mov_b64_e32 v[126:127], 0
	v_mov_b64_e32 v[128:129], 0
	v_mov_b64_e32 v[130:131], 0
	v_mov_b64_e32 v[132:133], 0
	v_mov_b64_e32 v[134:135], 0
	v_mov_b64_e32 v[136:137], 0
	v_mov_b64_e32 v[138:139], 0
	v_mov_b64_e32 v[140:141], 0
	v_mov_b64_e32 v[142:143], 0

.LBB0_1054:
	s_ashr_i32 s23, s22, 31
	s_lshl_b64 s[26:27], s[22:23], 19
	s_add_u32 s26, s94, s26
	s_addc_u32 s27, s95, s27
	s_and_b64 s[28:29], s[4:5], exec
	s_cselect_b32 s23, s27, s35
	s_cselect_b32 s62, s26, s34
	s_ashr_i32 s21, s20, 31
	s_lshl_b64 s[28:29], s[20:21], 19
	s_add_u32 s28, s42, s28
	s_addc_u32 s29, s43, s29
	s_and_b64 s[40:41], s[4:5], exec
	s_cselect_b32 s21, s29, s39
	s_cselect_b32 s63, s28, s38
	s_add_u32 s34, s34, 0x40080
	s_addc_u32 s35, s35, 0
	s_add_u32 s64, s38, 0x100
	v_mov_b32_e32 v0, 0
	s_addc_u32 s65, s39, 0
	s_mov_b32 s66, -2
	s_waitcnt lgkmcnt(0)
	v_mov_b32_e32 v1, 0
	v_mov_b64_e32 v[2:3], 0
	v_mov_b64_e32 v[4:5], 0
	v_mov_b64_e32 v[6:7], 0
	v_mov_b64_e32 v[8:9], 0
	v_mov_b64_e32 v[10:11], 0
	v_mov_b64_e32 v[12:13], 0
	v_mov_b64_e32 v[14:15], 0
	v_mov_b64_e32 v[16:17], 0
	v_mov_b64_e32 v[18:19], 0
	v_mov_b64_e32 v[20:21], 0
	v_mov_b64_e32 v[22:23], 0
	v_mov_b64_e32 v[24:25], 0
	v_mov_b64_e32 v[26:27], 0
	v_mov_b64_e32 v[28:29], 0
	v_mov_b64_e32 v[30:31], 0
	v_mov_b64_e32 v[32:33], 0
	v_mov_b64_e32 v[34:35], 0
	v_mov_b64_e32 v[36:37], 0
	v_mov_b64_e32 v[38:39], 0
	v_mov_b64_e32 v[40:41], 0
	v_mov_b64_e32 v[42:43], 0
	v_mov_b64_e32 v[44:45], 0
	v_mov_b64_e32 v[46:47], 0
	v_mov_b64_e32 v[48:49], 0
	v_mov_b64_e32 v[50:51], 0
	v_mov_b64_e32 v[52:53], 0
	v_mov_b64_e32 v[54:55], 0
	v_mov_b64_e32 v[56:57], 0
	v_mov_b64_e32 v[58:59], 0
	v_mov_b64_e32 v[60:61], 0
	v_mov_b64_e32 v[62:63], 0
	v_mov_b64_e32 v[64:65], 0
	v_mov_b64_e32 v[66:67], 0
	v_mov_b64_e32 v[72:73], 0
	v_mov_b64_e32 v[74:75], 0
	v_mov_b64_e32 v[88:89], 0
	v_mov_b64_e32 v[90:91], 0
	v_mov_b64_e32 v[92:93], 0
	v_mov_b64_e32 v[94:95], 0
	v_mov_b64_e32 v[96:97], 0
	v_mov_b64_e32 v[98:99], 0
	v_mov_b64_e32 v[100:101], 0
	v_mov_b64_e32 v[102:103], 0
	v_mov_b64_e32 v[104:105], 0
	v_mov_b64_e32 v[106:107], 0
	v_mov_b64_e32 v[108:109], 0
	v_mov_b64_e32 v[110:111], 0
	v_mov_b64_e32 v[112:113], 0
	v_mov_b64_e32 v[114:115], 0
	v_mov_b64_e32 v[116:117], 0
	v_mov_b64_e32 v[118:119], 0
	v_mov_b64_e32 v[120:121], 0
	v_mov_b64_e32 v[122:123], 0
	v_mov_b64_e32 v[124:125], 0
	v_mov_b64_e32 v[126:127], 0
	v_mov_b64_e32 v[128:129], 0
	v_mov_b64_e32 v[130:131], 0
	v_mov_b64_e32 v[132:133], 0
	v_mov_b64_e32 v[134:135], 0
	v_mov_b64_e32 v[136:137], 0
	v_mov_b64_e32 v[138:139], 0
	v_mov_b64_e32 v[140:141], 0
	v_mov_b64_e32 v[142:143], 0

.LBB0_1074:
	s_ashr_i32 s27, s26, 31
	s_lshl_b64 s[28:29], s[26:27], 18
	s_add_u32 s28, s53, s28
	s_addc_u32 s29, s54, s29
	s_and_b64 s[30:31], s[6:7], exec
	s_cselect_b32 s27, s29, s39
	s_cselect_b32 s66, s28, s38
	s_ashr_i32 s23, s22, 31
	s_lshl_b64 s[30:31], s[22:23], 18
	s_add_u32 s30, s55, s30
	s_addc_u32 s31, s56, s31
	s_and_b64 s[42:43], s[6:7], exec
	s_cselect_b32 s23, s31, s41
	s_cselect_b32 s67, s30, s40
	s_add_u32 s38, s38, 0x20080
	s_addc_u32 s39, s39, 0
	s_add_u32 s68, s40, 0x100
	v_mov_b32_e32 v0, 0
	s_addc_u32 s69, s41, 0
	s_mov_b32 s70, -2
	s_waitcnt lgkmcnt(0)
	v_mov_b32_e32 v1, 0
	v_mov_b64_e32 v[2:3], 0
	v_mov_b64_e32 v[4:5], 0
	v_mov_b64_e32 v[6:7], 0
	v_mov_b64_e32 v[8:9], 0
	v_mov_b64_e32 v[10:11], 0
	v_mov_b64_e32 v[12:13], 0
	v_mov_b64_e32 v[14:15], 0
	v_mov_b64_e32 v[16:17], 0
	v_mov_b64_e32 v[18:19], 0
	v_mov_b64_e32 v[20:21], 0
	v_mov_b64_e32 v[22:23], 0
	v_mov_b64_e32 v[24:25], 0
	v_mov_b64_e32 v[26:27], 0
	v_mov_b64_e32 v[28:29], 0
	v_mov_b64_e32 v[30:31], 0
	v_mov_b64_e32 v[32:33], 0
	v_mov_b64_e32 v[34:35], 0
	v_mov_b64_e32 v[36:37], 0
	v_mov_b64_e32 v[38:39], 0
	v_mov_b64_e32 v[40:41], 0
	v_mov_b64_e32 v[42:43], 0
	v_mov_b64_e32 v[44:45], 0
	v_mov_b64_e32 v[46:47], 0
	v_mov_b64_e32 v[48:49], 0
	v_mov_b64_e32 v[50:51], 0
	v_mov_b64_e32 v[52:53], 0
	v_mov_b64_e32 v[54:55], 0
	v_mov_b64_e32 v[56:57], 0
	v_mov_b64_e32 v[58:59], 0
	v_mov_b64_e32 v[60:61], 0
	v_mov_b64_e32 v[62:63], 0
	v_mov_b64_e32 v[64:65], 0
	v_mov_b64_e32 v[66:67], 0
	v_mov_b64_e32 v[68:69], 0
	v_mov_b64_e32 v[70:71], 0
	v_mov_b64_e32 v[72:73], 0
	v_mov_b64_e32 v[74:75], 0
	v_mov_b64_e32 v[76:77], 0
	v_mov_b64_e32 v[78:79], 0
	v_mov_b64_e32 v[80:81], 0
	v_mov_b64_e32 v[82:83], 0
	v_mov_b64_e32 v[84:85], 0
	v_mov_b64_e32 v[86:87], 0
	v_mov_b64_e32 v[88:89], 0
	v_mov_b64_e32 v[90:91], 0
	v_mov_b64_e32 v[92:93], 0
	v_mov_b64_e32 v[94:95], 0
	v_mov_b64_e32 v[96:97], 0
	v_mov_b64_e32 v[98:99], 0
	v_mov_b64_e32 v[100:101], 0
	v_mov_b64_e32 v[102:103], 0
	v_mov_b64_e32 v[104:105], 0
	v_mov_b64_e32 v[106:107], 0
	v_mov_b64_e32 v[108:109], 0
	v_mov_b64_e32 v[110:111], 0
	v_mov_b64_e32 v[112:113], 0
	v_mov_b64_e32 v[114:115], 0
	v_mov_b64_e32 v[116:117], 0
	v_mov_b64_e32 v[118:119], 0
	v_mov_b64_e32 v[120:121], 0
	v_mov_b64_e32 v[122:123], 0
	v_mov_b64_e32 v[124:125], 0
	v_mov_b64_e32 v[126:127], 0

.LBB0_1094:
	s_ashr_i32 s27, s26, 31
	s_lshl_b64 s[28:29], s[26:27], 19
	s_add_u32 s28, s94, s28
	s_addc_u32 s29, s95, s29
	s_and_b64 s[30:31], s[6:7], exec
	s_cselect_b32 s27, s29, s39
	s_cselect_b32 s64, s28, s38
	s_ashr_i32 s23, s22, 31
	s_lshl_b64 s[30:31], s[22:23], 19
	s_add_u32 s30, s53, s30
	s_addc_u32 s31, s54, s31
	s_and_b64 s[42:43], s[6:7], exec
	s_cselect_b32 s23, s31, s41
	s_cselect_b32 s65, s30, s40
	s_add_u32 s38, s38, 0x40080
	s_addc_u32 s39, s39, 0
	s_add_u32 s66, s40, 0x100
	v_mov_b32_e32 v0, 0
	s_addc_u32 s67, s41, 0
	s_mov_b32 s68, -2
	s_waitcnt lgkmcnt(0)
	v_mov_b32_e32 v1, 0
	v_mov_b64_e32 v[2:3], 0
	v_mov_b64_e32 v[4:5], 0
	v_mov_b64_e32 v[6:7], 0
	v_mov_b64_e32 v[8:9], 0
	v_mov_b64_e32 v[10:11], 0
	v_mov_b64_e32 v[12:13], 0
	v_mov_b64_e32 v[14:15], 0
	v_mov_b64_e32 v[16:17], 0
	v_mov_b64_e32 v[18:19], 0
	v_mov_b64_e32 v[20:21], 0
	v_mov_b64_e32 v[22:23], 0
	v_mov_b64_e32 v[24:25], 0
	v_mov_b64_e32 v[26:27], 0
	v_mov_b64_e32 v[28:29], 0
	v_mov_b64_e32 v[30:31], 0
	v_mov_b64_e32 v[32:33], 0
	v_mov_b64_e32 v[34:35], 0
	v_mov_b64_e32 v[36:37], 0
	v_mov_b64_e32 v[38:39], 0
	v_mov_b64_e32 v[40:41], 0
	v_mov_b64_e32 v[42:43], 0
	v_mov_b64_e32 v[44:45], 0
	v_mov_b64_e32 v[46:47], 0
	v_mov_b64_e32 v[48:49], 0
	v_mov_b64_e32 v[50:51], 0
	v_mov_b64_e32 v[52:53], 0
	v_mov_b64_e32 v[54:55], 0
	v_mov_b64_e32 v[56:57], 0
	v_mov_b64_e32 v[58:59], 0
	v_mov_b64_e32 v[60:61], 0
	v_mov_b64_e32 v[62:63], 0
	v_mov_b64_e32 v[64:65], 0
	v_mov_b64_e32 v[66:67], 0
	v_mov_b64_e32 v[72:73], 0
	v_mov_b64_e32 v[74:75], 0
	v_mov_b64_e32 v[88:89], 0
	v_mov_b64_e32 v[90:91], 0
	v_mov_b64_e32 v[92:93], 0
	v_mov_b64_e32 v[94:95], 0
	v_mov_b64_e32 v[96:97], 0
	v_mov_b64_e32 v[98:99], 0
	v_mov_b64_e32 v[100:101], 0
	v_mov_b64_e32 v[102:103], 0
	v_mov_b64_e32 v[104:105], 0
	v_mov_b64_e32 v[106:107], 0
	v_mov_b64_e32 v[108:109], 0
	v_mov_b64_e32 v[110:111], 0
	v_mov_b64_e32 v[112:113], 0
	v_mov_b64_e32 v[114:115], 0
	v_mov_b64_e32 v[116:117], 0
	v_mov_b64_e32 v[118:119], 0
	v_mov_b64_e32 v[120:121], 0
	v_mov_b64_e32 v[122:123], 0
	v_mov_b64_e32 v[124:125], 0
	v_mov_b64_e32 v[126:127], 0
	v_mov_b64_e32 v[128:129], 0
	v_mov_b64_e32 v[130:131], 0
	v_mov_b64_e32 v[132:133], 0
	v_mov_b64_e32 v[134:135], 0
	v_mov_b64_e32 v[136:137], 0
	v_mov_b64_e32 v[138:139], 0
	v_mov_b64_e32 v[140:141], 0
	v_mov_b64_e32 v[142:143], 0

.LBB0_1114:
	s_ashr_i32 s17, s16, 31
	s_lshl_b64 s[20:21], s[16:17], 18
	s_add_u32 s20, s34, s20
	s_addc_u32 s21, s35, s21
	s_and_b64 s[22:23], s[4:5], exec
	s_cselect_b32 s17, s21, s27
	s_cselect_b32 s48, s20, s26
	s_ashr_i32 s15, s14, 31
	s_lshl_b64 s[22:23], s[14:15], 18
	s_add_u32 s22, s38, s22
	s_addc_u32 s23, s39, s23
	s_and_b64 s[30:31], s[4:5], exec
	s_cselect_b32 s15, s23, s29
	s_cselect_b32 s49, s22, s28
	s_add_u32 s26, s26, 0x20080
	s_addc_u32 s27, s27, 0
	s_add_u32 s53, s28, 0x100
	v_mov_b32_e32 v0, 0
	s_addc_u32 s54, s29, 0
	s_mov_b32 s55, -2
	s_waitcnt lgkmcnt(0)
	v_mov_b32_e32 v1, 0
	v_mov_b64_e32 v[2:3], 0
	v_mov_b64_e32 v[4:5], 0
	v_mov_b64_e32 v[6:7], 0
	v_mov_b64_e32 v[8:9], 0
	v_mov_b64_e32 v[10:11], 0
	v_mov_b64_e32 v[12:13], 0
	v_mov_b64_e32 v[14:15], 0
	v_mov_b64_e32 v[16:17], 0
	v_mov_b64_e32 v[18:19], 0
	v_mov_b64_e32 v[20:21], 0
	v_mov_b64_e32 v[22:23], 0
	v_mov_b64_e32 v[24:25], 0
	v_mov_b64_e32 v[26:27], 0
	v_mov_b64_e32 v[28:29], 0
	v_mov_b64_e32 v[30:31], 0
	v_mov_b64_e32 v[32:33], 0
	v_mov_b64_e32 v[34:35], 0
	v_mov_b64_e32 v[36:37], 0
	v_mov_b64_e32 v[38:39], 0
	v_mov_b64_e32 v[40:41], 0
	v_mov_b64_e32 v[42:43], 0
	v_mov_b64_e32 v[44:45], 0
	v_mov_b64_e32 v[46:47], 0
	v_mov_b64_e32 v[48:49], 0
	v_mov_b64_e32 v[50:51], 0
	v_mov_b64_e32 v[52:53], 0
	v_mov_b64_e32 v[54:55], 0
	v_mov_b64_e32 v[56:57], 0
	v_mov_b64_e32 v[58:59], 0
	v_mov_b64_e32 v[60:61], 0
	v_mov_b64_e32 v[62:63], 0
	v_mov_b64_e32 v[64:65], 0
	v_mov_b64_e32 v[66:67], 0
	v_mov_b64_e32 v[68:69], 0
	v_mov_b64_e32 v[70:71], 0
	v_mov_b64_e32 v[72:73], 0
	v_mov_b64_e32 v[74:75], 0
	v_mov_b64_e32 v[76:77], 0
	v_mov_b64_e32 v[78:79], 0
	v_mov_b64_e32 v[80:81], 0
	v_mov_b64_e32 v[82:83], 0
	v_mov_b64_e32 v[84:85], 0
	v_mov_b64_e32 v[86:87], 0
	v_mov_b64_e32 v[88:89], 0
	v_mov_b64_e32 v[90:91], 0
	v_mov_b64_e32 v[92:93], 0
	v_mov_b64_e32 v[94:95], 0
	v_mov_b64_e32 v[96:97], 0
	v_mov_b64_e32 v[98:99], 0
	v_mov_b64_e32 v[100:101], 0
	v_mov_b64_e32 v[102:103], 0
	v_mov_b64_e32 v[104:105], 0
	v_mov_b64_e32 v[106:107], 0
	v_mov_b64_e32 v[108:109], 0
	v_mov_b64_e32 v[110:111], 0
	v_mov_b64_e32 v[112:113], 0
	v_mov_b64_e32 v[114:115], 0
	v_mov_b64_e32 v[116:117], 0
	v_mov_b64_e32 v[118:119], 0
	v_mov_b64_e32 v[120:121], 0
	v_mov_b64_e32 v[122:123], 0
	v_mov_b64_e32 v[124:125], 0
	v_mov_b64_e32 v[126:127], 0

.LBB0_1191:
	s_ashr_i32 s19, s18, 31
	s_lshl_b64 s[20:21], s[18:19], 19
	s_add_u32 s20, s3, s20
	s_addc_u32 s21, s38, s21
	s_and_b64 s[22:23], s[4:5], exec
	s_cselect_b32 s19, s21, s29
	s_cselect_b32 s25, s20, s28
	s_ashr_i32 s17, s16, 31
	s_lshl_b64 s[22:23], s[16:17], 19
	s_add_u32 s22, s39, s22
	s_addc_u32 s23, s40, s23
	s_and_b64 s[34:35], s[4:5], exec
	s_cselect_b32 s17, s23, s31
	s_cselect_b32 s53, s22, s30
	s_add_u32 s28, s28, 0x40080
	s_addc_u32 s29, s29, 0
	s_add_u32 s54, s30, 0x100
	v_mov_b32_e32 v0, 0
	s_addc_u32 s55, s31, 0
	s_mov_b32 s56, -2
	s_waitcnt lgkmcnt(0)
	s_waitcnt lgkmcnt(0)
	v_mov_b32_e32 v1, 0
	v_mov_b64_e32 v[2:3], 0
	v_mov_b64_e32 v[4:5], 0
	v_mov_b64_e32 v[6:7], 0
	v_mov_b64_e32 v[8:9], 0
	v_mov_b64_e32 v[10:11], 0
	v_mov_b64_e32 v[12:13], 0
	v_mov_b64_e32 v[14:15], 0
	v_mov_b64_e32 v[16:17], 0
	v_mov_b64_e32 v[18:19], 0
	v_mov_b64_e32 v[20:21], 0
	v_mov_b64_e32 v[22:23], 0
	v_mov_b64_e32 v[24:25], 0
	v_mov_b64_e32 v[26:27], 0
	v_mov_b64_e32 v[28:29], 0
	v_mov_b64_e32 v[30:31], 0
	v_mov_b64_e32 v[32:33], 0
	v_mov_b64_e32 v[34:35], 0
	v_mov_b64_e32 v[36:37], 0
	v_mov_b64_e32 v[38:39], 0
	v_mov_b64_e32 v[40:41], 0
	v_mov_b64_e32 v[42:43], 0
	v_mov_b64_e32 v[44:45], 0
	v_mov_b64_e32 v[46:47], 0
	v_mov_b64_e32 v[48:49], 0
	v_mov_b64_e32 v[50:51], 0
	v_mov_b64_e32 v[52:53], 0
	v_mov_b64_e32 v[54:55], 0
	v_mov_b64_e32 v[56:57], 0
	v_mov_b64_e32 v[58:59], 0
	v_mov_b64_e32 v[60:61], 0
	v_mov_b64_e32 v[62:63], 0
	v_mov_b64_e32 v[64:65], 0
	v_mov_b64_e32 v[66:67], 0
	v_mov_b64_e32 v[68:69], 0
	v_mov_b64_e32 v[70:71], 0
	v_mov_b64_e32 v[72:73], 0
	v_mov_b64_e32 v[74:75], 0
	v_mov_b64_e32 v[76:77], 0
	v_mov_b64_e32 v[78:79], 0
	v_mov_b64_e32 v[80:81], 0
	v_mov_b64_e32 v[82:83], 0
	v_mov_b64_e32 v[84:85], 0
	v_mov_b64_e32 v[86:87], 0
	v_mov_b64_e32 v[88:89], 0
	v_mov_b64_e32 v[90:91], 0
	v_mov_b64_e32 v[92:93], 0
	v_mov_b64_e32 v[94:95], 0
	v_mov_b64_e32 v[96:97], 0
	v_mov_b64_e32 v[98:99], 0
	v_mov_b64_e32 v[100:101], 0
	v_mov_b64_e32 v[102:103], 0
	v_mov_b64_e32 v[104:105], 0
	v_mov_b64_e32 v[106:107], 0
	v_mov_b64_e32 v[108:109], 0
	v_mov_b64_e32 v[110:111], 0
	v_mov_b64_e32 v[112:113], 0
	v_mov_b64_e32 v[114:115], 0
	v_mov_b64_e32 v[116:117], 0
	v_mov_b64_e32 v[118:119], 0
	v_mov_b64_e32 v[120:121], 0
	v_mov_b64_e32 v[122:123], 0
	v_mov_b64_e32 v[124:125], 0
	v_mov_b64_e32 v[126:127], 0

.LBB0_1348:
	v_mov_b32_e32 v0, 0
	s_mov_b32 s21, 0
	s_mov_b64 s[34:35], -1
	s_mov_b64 s[36:37], 0
	s_waitcnt vmcnt(0)
	v_mov_b32_e32 v1, 0
	v_mov_b64_e32 v[2:3], 0
	v_mov_b64_e32 v[4:5], 0
	v_mov_b64_e32 v[6:7], 0
	v_mov_b64_e32 v[8:9], 0
	v_mov_b64_e32 v[10:11], 0
	v_mov_b64_e32 v[12:13], 0
	v_mov_b64_e32 v[14:15], 0
	v_mov_b64_e32 v[16:17], 0
	v_mov_b64_e32 v[18:19], 0
	v_mov_b64_e32 v[20:21], 0
	v_mov_b64_e32 v[22:23], 0
	v_mov_b64_e32 v[24:25], 0
	v_mov_b64_e32 v[26:27], 0
	v_mov_b64_e32 v[28:29], 0
	v_mov_b64_e32 v[30:31], 0
	v_mov_b64_e32 v[32:33], 0
	v_mov_b64_e32 v[34:35], 0
	v_mov_b64_e32 v[36:37], 0
	v_mov_b64_e32 v[38:39], 0
	v_mov_b64_e32 v[40:41], 0
	v_mov_b64_e32 v[42:43], 0
	v_mov_b64_e32 v[44:45], 0
	v_mov_b64_e32 v[46:47], 0
	v_mov_b64_e32 v[48:49], 0
	v_mov_b64_e32 v[50:51], 0
	v_mov_b64_e32 v[52:53], 0
	v_mov_b64_e32 v[54:55], 0
	v_mov_b64_e32 v[56:57], 0
	v_mov_b64_e32 v[58:59], 0
	v_mov_b64_e32 v[60:61], 0
	v_mov_b64_e32 v[62:63], 0
	v_mov_b64_e32 v[64:65], 0
	v_mov_b64_e32 v[66:67], 0
	v_mov_b64_e32 v[68:69], 0
	v_mov_b64_e32 v[70:71], 0
	v_mov_b64_e32 v[72:73], 0
	v_mov_b64_e32 v[74:75], 0
	v_mov_b64_e32 v[76:77], 0
	v_mov_b64_e32 v[78:79], 0
	v_mov_b64_e32 v[80:81], 0
	v_mov_b64_e32 v[82:83], 0
	v_mov_b64_e32 v[84:85], 0
	v_mov_b64_e32 v[86:87], 0
	v_mov_b64_e32 v[88:89], 0
	v_mov_b64_e32 v[90:91], 0
	v_mov_b64_e32 v[92:93], 0
	v_mov_b64_e32 v[94:95], 0
	v_mov_b64_e32 v[96:97], 0
	v_mov_b64_e32 v[98:99], 0
	v_mov_b64_e32 v[100:101], 0
	v_mov_b64_e32 v[102:103], 0
	v_mov_b64_e32 v[104:105], 0
	v_mov_b64_e32 v[106:107], 0
	v_mov_b64_e32 v[108:109], 0
	v_mov_b64_e32 v[110:111], 0
	v_mov_b64_e32 v[112:113], 0
	v_mov_b64_e32 v[114:115], 0
	v_mov_b64_e32 v[116:117], 0
	v_mov_b64_e32 v[118:119], 0
	v_mov_b64_e32 v[120:121], 0
	v_mov_b64_e32 v[122:123], 0
	v_mov_b64_e32 v[124:125], 0
	v_mov_b64_e32 v[126:127], 0
